# lever 1 (counted waits): row passes a, b request the bf16 sublayer-output quads before the f32 residual row and wait for the residual row only at its first use
# speedup vs baseline: 1.0081x; 1.0051x over previous
.LBB0_289:
	v_lshl_add_u64 v[0:1], s[16:17], 0, v[192:193]
	v_lshl_add_u64 v[32:33], s[20:21], 0, v[52:53]
	v_add_co_u32_e32 v34, vcc, 0x1ba00000, v32
	s_nop 1
	v_addc_co_u32_e32 v35, vcc, 0, v33, vcc
	global_load_dwordx4 v[64:67], v[34:35], off
	global_load_dwordx4 v[68:71], v[34:35], off offset:1024
	global_load_dwordx4 v[58:61], v[34:35], off offset:2048
	global_load_dwordx4 v[88:91], v[34:35], off offset:3072
	v_add_co_u32_e32 v4, vcc, 0x1000, v0
	s_nop 1
	v_addc_co_u32_e32 v5, vcc, 0, v1, vcc
	global_load_dwordx4 v[8:11], v[0:1], off offset:16
	global_load_dwordx4 v[12:15], v[0:1], off
	global_load_dwordx4 v[16:19], v[0:1], off offset:2064
	global_load_dwordx4 v[20:23], v[0:1], off offset:2048
	v_lshl_add_u64 v[2:3], v[0:1], 0, s[28:29]
	v_lshl_add_u64 v[0:1], v[0:1], 0, s[26:27]
	global_load_dwordx4 v[28:31], v[4:5], off
	global_load_dwordx4 v[24:27], v[2:3], off offset:16
	s_nop 0
	global_load_dwordx4 v[4:7], v[4:5], off offset:2048
	s_nop 0
	global_load_dwordx4 v[0:3], v[0:1], off offset:16
	s_nop 0
	s_mov_b32 s4, 0xf800000
	s_waitcnt vmcnt(11)
	v_and_b32_e32 v75, 0xffff0000, v66
	v_and_b32_e32 v74, 0xffff0000, v64
	v_and_b32_e32 v79, 0xffff0000, v67
	v_and_b32_e32 v78, 0xffff0000, v65
	v_lshlrev_b32_e32 v73, 16, v66
	v_lshlrev_b32_e32 v72, 16, v64
	v_lshlrev_b32_e32 v77, 16, v67
	v_lshlrev_b32_e32 v76, 16, v65
	v_pk_mul_f32 v[34:35], v[74:75], v[74:75]
	v_pk_mul_f32 v[64:65], v[78:79], v[78:79]
	v_pk_fma_f32 v[34:35], v[72:73], v[72:73], v[34:35]
	v_pk_fma_f32 v[64:65], v[76:77], v[76:77], v[64:65]
	s_waitcnt vmcnt(10)
	v_lshlrev_b32_e32 v32, 16, v70
	v_pk_add_f32 v[34:35], v[34:35], v[64:65]
	v_and_b32_e32 v33, 0xffff0000, v70
	v_pk_add_f32 v[64:65], v[34:35], v[34:35] op_sel_hi:[0,1]
	v_lshlrev_b32_e32 v35, 16, v69
	v_lshlrev_b32_e32 v34, 16, v68
	v_and_b32_e32 v69, 0xffff0000, v69
	v_and_b32_e32 v68, 0xffff0000, v68
	s_waitcnt vmcnt(9)
	v_lshlrev_b32_e32 v36, 16, v58
	v_pk_mul_f32 v[66:67], v[68:69], v[68:69]
	v_lshlrev_b32_e32 v70, 16, v71
	s_waitcnt vmcnt(8)
	v_lshlrev_b32_e32 v56, 16, v90
	v_and_b32_e32 v85, 0xffff0000, v90
	v_lshlrev_b32_e32 v54, 16, v91
	v_and_b32_e32 v55, 0xffff0000, v91
	v_pk_fma_f32 v[66:67], v[34:35], v[34:35], v[66:67]
	v_mul_f32_e32 v37, v32, v32
	v_mul_f32_e32 v91, v33, v33
	v_and_b32_e32 v71, 0xffff0000, v71
	v_mul_f32_e32 v62, v70, v70
	v_mov_b32_e32 v90, v36
	v_and_b32_e32 v86, 0xffff0000, v58
	v_lshlrev_b32_e32 v38, 16, v59
	v_and_b32_e32 v39, 0xffff0000, v59
	v_pk_add_f32 v[66:67], v[66:67], v[66:67] op_sel_hi:[0,1]
	v_pk_fma_f32 v[92:93], v[70:71], v[70:71], v[62:63] op_sel_hi:[1,1,0]
	v_pk_add_f32 v[90:91], v[36:37], v[90:91]
	v_mul_f32_e32 v92, v86, v86
	v_mul_f32_e32 v64, v38, v38
	v_mul_f32_e32 v66, v39, v39
	v_mul_f32_e32 v94, v36, v36
	v_mov_b32_e32 v95, v91
	v_pk_add_f32 v[90:91], v[94:95], v[92:93]
	v_pk_add_f32 v[64:65], v[64:65], v[66:67]
	v_and_b32_e32 v67, 0xffff0000, v61
	v_pk_add_f32 v[64:65], v[90:91], v[64:65]
	v_and_b32_e32 v66, 0xffff0000, v60
	v_pk_add_f32 v[90:91], v[64:65], v[64:65] op_sel_hi:[0,1]
	v_lshlrev_b32_e32 v65, 16, v61
	v_lshlrev_b32_e32 v64, 16, v60
	v_pk_mul_f32 v[60:61], v[66:67], v[66:67]
	v_lshlrev_b32_e32 v58, 16, v88
	v_pk_fma_f32 v[60:61], v[64:65], v[64:65], v[60:61]
	v_and_b32_e32 v59, 0xffff0000, v88
	v_pk_add_f32 v[92:93], v[60:61], v[60:61] op_sel_hi:[0,1]
	v_lshlrev_b32_e32 v60, 16, v89
	v_mul_f32_e32 v57, v58, v58
	v_mul_f32_e32 v95, v59, v59
	v_and_b32_e32 v61, 0xffff0000, v89
	v_mul_f32_e32 v62, v60, v60
	v_mov_b32_e32 v94, v56
	v_pk_fma_f32 v[88:89], v[60:61], v[60:61], v[62:63] op_sel_hi:[1,1,0]
	v_pk_add_f32 v[94:95], v[56:57], v[94:95]
	v_mul_f32_e32 v88, v85, v85
	v_mul_f32_e32 v92, v54, v54
	v_mul_f32_e32 v90, v55, v55
	v_mul_f32_e32 v96, v56, v56
	v_mov_b32_e32 v97, v95
	v_pk_add_f32 v[88:89], v[96:97], v[88:89]
	v_pk_add_f32 v[90:91], v[92:93], v[90:91]
	v_mov_b32_e32 v96, v72
	v_pk_add_f32 v[88:89], v[88:89], v[90:91]
	v_mov_b32_e32 v97, v74
	v_add_f32_e32 v37, v88, v89
	ds_bpermute_b32 v57, v63, v37
	v_mov_b32_e32 v74, v73
	s_waitcnt lgkmcnt(0)
	v_add_f32_e32 v37, v37, v57
	ds_bpermute_b32 v57, v80, v37
	s_waitcnt lgkmcnt(0)
	v_add_f32_e32 v37, v37, v57
	ds_bpermute_b32 v57, v81, v37
	s_waitcnt lgkmcnt(0)
	v_add_f32_e32 v37, v37, v57
	ds_bpermute_b32 v57, v82, v37
	s_waitcnt lgkmcnt(0)
	v_add_f32_e32 v37, v37, v57
	ds_bpermute_b32 v57, v83, v37
	s_waitcnt lgkmcnt(0)
	v_add_f32_e32 v37, v37, v57
	ds_bpermute_b32 v57, v84, v37
	s_waitcnt lgkmcnt(0)
	v_add_f32_e32 v37, v37, v57
	v_fmamk_f32 v37, v37, 0x3a000000, v219
	v_cmp_gt_f32_e32 vcc, s4, v37
	v_mul_f32_e32 v57, 0x4f800000, v37
	s_nop 0
	v_cndmask_b32_e32 v37, v37, v57, vcc
	v_sqrt_f32_e32 v57, v37
	s_nop 0
	v_add_u32_e32 v62, -1, v57
	v_fma_f32 v87, -v62, v57, v37
	v_cmp_ge_f32_e64 s[6:7], 0, v87
	v_add_u32_e32 v87, 1, v57
	s_nop 0
	v_cndmask_b32_e64 v62, v57, v62, s[6:7]
	v_fma_f32 v57, -v87, v57, v37
	v_cmp_lt_f32_e64 s[6:7], 0, v57
	s_nop 1
	v_cndmask_b32_e64 v57, v62, v87, s[6:7]
	v_mul_f32_e32 v62, 0x37800000, v57
	v_cndmask_b32_e32 v57, v57, v62, vcc
	v_cmp_class_f32_e32 vcc, v37, v220
	s_nop 1
	v_cndmask_b32_e32 v37, v57, v37, vcc
	v_div_scale_f32 v57, s[4:5], v37, v37, 0.5
	v_rcp_f32_e32 v62, v57
	s_nop 0
	v_fma_f32 v87, -v57, v62, 1.0
	v_fmac_f32_e32 v62, v87, v62
	v_div_scale_f32 v87, vcc, 0.5, v37, 0.5
	v_mul_f32_e32 v88, v87, v62
	v_fma_f32 v89, -v57, v88, v87
	v_fmac_f32_e32 v88, v89, v62
	v_fma_f32 v57, -v57, v88, v87
	v_div_fmas_f32 v57, v57, v62, v88
	v_mov_b64_e32 v[88:89], v[100:101]
	v_mov_b64_e32 v[90:91], v[102:103]
	v_mov_b64_e32 v[92:93], v[104:105]
	v_mov_b64_e32 v[94:95], v[106:107]
	v_div_fixup_f32 v62, v57, v37, 0.5
	s_waitcnt vmcnt(0)
	v_mov_b32_e32 v37, v86
	v_mov_b32_e32 v57, v85
	s_andn2_b64 vcc, exec, s[10:11]
	v_pk_mul_f32 v[72:73], v[88:89], v[74:75]
	v_pk_mul_f32 v[92:93], v[92:93], v[96:97]
	v_mov_b32_e32 v97, v78
	v_mov_b32_e32 v78, v77
	v_pk_mul_f32 v[74:75], v[90:91], v[78:79]
	v_mov_b32_e32 v96, v76
	v_pk_fma_f32 v[10:11], v[74:75], v[62:63], v[10:11] op_sel_hi:[1,0,1]
	v_pk_fma_f32 v[8:9], v[72:73], v[62:63], v[8:9] op_sel_hi:[1,0,1]
	v_mov_b64_e32 v[72:73], v[108:109]
	v_mov_b64_e32 v[74:75], v[110:111]
	v_mov_b64_e32 v[76:77], v[112:113]
	v_mov_b64_e32 v[78:79], v[114:115]
	v_mov_b32_e32 v89, v68
	v_mov_b32_e32 v68, v35
	v_mov_b32_e32 v88, v34
	v_pk_mul_f32 v[94:95], v[94:95], v[96:97]
	v_pk_fma_f32 v[12:13], v[92:93], v[62:63], v[12:13] op_sel_hi:[1,0,1]
	v_pk_fma_f32 v[14:15], v[94:95], v[62:63], v[14:15] op_sel_hi:[1,0,1]
	v_pk_mul_f32 v[32:33], v[72:73], v[32:33]
	v_pk_mul_f32 v[34:35], v[78:79], v[68:69]
	v_pk_fma_f32 v[16:17], v[32:33], v[62:63], v[16:17] op_sel_hi:[1,0,1]
	v_pk_fma_f32 v[22:23], v[34:35], v[62:63], v[22:23] op_sel_hi:[1,0,1]
	v_pk_mul_f32 v[34:35], v[74:75], v[70:71]
	v_pk_mul_f32 v[76:77], v[76:77], v[88:89]
	v_pk_fma_f32 v[18:19], v[34:35], v[62:63], v[18:19] op_sel_hi:[1,0,1]
	v_mov_b64_e32 v[32:33], v[116:117]
	v_mov_b64_e32 v[34:35], v[118:119]
	v_mov_b64_e32 v[68:69], v[120:121]
	v_mov_b64_e32 v[70:71], v[122:123]
	v_pk_fma_f32 v[20:21], v[76:77], v[62:63], v[20:21] op_sel_hi:[1,0,1]
	v_pk_mul_f32 v[36:37], v[68:69], v[36:37]
	s_nop 0
	v_pk_fma_f32 v[28:29], v[36:37], v[62:63], v[28:29] op_sel_hi:[1,0,1]
	v_mov_b32_e32 v36, v64
	v_mov_b32_e32 v37, v66
	v_mov_b32_e32 v66, v65
	v_pk_mul_f32 v[38:39], v[70:71], v[38:39]
	v_pk_mul_f32 v[32:33], v[32:33], v[36:37]
	v_pk_mul_f32 v[34:35], v[34:35], v[66:67]
	v_pk_fma_f32 v[30:31], v[38:39], v[62:63], v[30:31] op_sel_hi:[1,0,1]
	v_pk_fma_f32 v[26:27], v[34:35], v[62:63], v[26:27] op_sel_hi:[1,0,1]
	v_pk_fma_f32 v[24:25], v[32:33], v[62:63], v[24:25] op_sel_hi:[1,0,1]
	v_mov_b64_e32 v[32:33], v[124:125]
	v_mov_b64_e32 v[34:35], v[126:127]
	v_mov_b64_e32 v[36:37], v[128:129]
	v_mov_b64_e32 v[38:39], v[130:131]
	v_pk_mul_f32 v[32:33], v[32:33], v[56:57]
	v_pk_mul_f32 v[36:37], v[36:37], v[58:59]
	v_pk_mul_f32 v[38:39], v[38:39], v[60:61]
	v_pk_mul_f32 v[34:35], v[34:35], v[54:55]
	v_pk_fma_f32 v[6:7], v[38:39], v[62:63], v[6:7] op_sel_hi:[1,0,1]
	v_pk_fma_f32 v[4:5], v[36:37], v[62:63], v[4:5] op_sel_hi:[1,0,1]
	v_pk_fma_f32 v[2:3], v[34:35], v[62:63], v[2:3] op_sel_hi:[1,0,1]
	v_pk_fma_f32 v[0:1], v[32:33], v[62:63], v[0:1] op_sel_hi:[1,0,1]
	s_cbranch_vccnz .LBB0_291
	v_lshl_add_u64 v[32:33], s[22:23], 0, v[192:193]
	global_store_dwordx4 v[32:33], v[12:15], off
	global_store_dwordx4 v[32:33], v[8:11], off offset:16
	global_store_dwordx4 v[32:33], v[20:23], off offset:2048
	global_store_dwordx4 v[32:33], v[16:19], off offset:2064
	v_add_co_u32_e32 v32, vcc, 0x1000, v32
	s_nop 1
	v_addc_co_u32_e32 v33, vcc, 0, v33, vcc
	global_store_dwordx4 v[32:33], v[28:31], off
	global_store_dwordx4 v[32:33], v[24:27], off offset:16
	global_store_dwordx4 v[32:33], v[4:7], off offset:2048
	global_store_dwordx4 v[32:33], v[0:3], off offset:2064

.LBB0_746:
	v_lshl_add_u64 v[0:1], s[12:13], 0, v[192:193]
	v_lshl_add_u64 v[32:33], s[16:17], 0, v[52:53]
	v_add_co_u32_e32 v34, vcc, 0x1ba00000, v32
	s_nop 1
	v_addc_co_u32_e32 v35, vcc, 0, v33, vcc
	global_load_dwordx4 v[64:67], v[34:35], off
	global_load_dwordx4 v[68:71], v[34:35], off offset:1024
	global_load_dwordx4 v[58:61], v[34:35], off offset:2048
	global_load_dwordx4 v[82:85], v[34:35], off offset:3072
	v_add_co_u32_e32 v4, vcc, 0x1000, v0
	s_nop 1
	v_addc_co_u32_e32 v5, vcc, 0, v1, vcc
	global_load_dwordx4 v[8:11], v[0:1], off offset:16
	global_load_dwordx4 v[12:15], v[0:1], off
	global_load_dwordx4 v[16:19], v[0:1], off offset:2064
	global_load_dwordx4 v[20:23], v[0:1], off offset:2048
	v_lshl_add_u64 v[2:3], v[0:1], 0, s[26:27]
	v_lshl_add_u64 v[0:1], v[0:1], 0, s[24:25]
	global_load_dwordx4 v[28:31], v[4:5], off
	global_load_dwordx4 v[24:27], v[2:3], off offset:16
	s_nop 0
	global_load_dwordx4 v[4:7], v[4:5], off offset:2048
	s_nop 0
	global_load_dwordx4 v[0:3], v[0:1], off offset:16
	s_nop 0
	s_mov_b32 s4, 0xf800000
	s_waitcnt vmcnt(11)
	v_and_b32_e32 v75, 0xffff0000, v66
	v_and_b32_e32 v74, 0xffff0000, v64
	v_and_b32_e32 v79, 0xffff0000, v67
	v_and_b32_e32 v78, 0xffff0000, v65
	v_lshlrev_b32_e32 v73, 16, v66
	v_lshlrev_b32_e32 v72, 16, v64
	v_lshlrev_b32_e32 v77, 16, v67
	v_lshlrev_b32_e32 v76, 16, v65
	v_pk_mul_f32 v[34:35], v[74:75], v[74:75]
	v_pk_mul_f32 v[64:65], v[78:79], v[78:79]
	v_pk_fma_f32 v[34:35], v[72:73], v[72:73], v[34:35]
	v_pk_fma_f32 v[64:65], v[76:77], v[76:77], v[64:65]
	s_waitcnt vmcnt(10)
	v_lshlrev_b32_e32 v32, 16, v70
	v_pk_add_f32 v[34:35], v[34:35], v[64:65]
	v_and_b32_e32 v33, 0xffff0000, v70
	v_pk_add_f32 v[64:65], v[34:35], v[34:35] op_sel_hi:[0,1]
	v_lshlrev_b32_e32 v35, 16, v69
	v_lshlrev_b32_e32 v34, 16, v68
	v_and_b32_e32 v69, 0xffff0000, v69
	v_and_b32_e32 v68, 0xffff0000, v68
	s_waitcnt vmcnt(9)
	v_lshlrev_b32_e32 v36, 16, v58
	v_pk_mul_f32 v[66:67], v[68:69], v[68:69]
	v_lshlrev_b32_e32 v70, 16, v71
	s_waitcnt vmcnt(8)
	v_lshlrev_b32_e32 v56, 16, v84
	v_and_b32_e32 v63, 0xffff0000, v84
	v_lshlrev_b32_e32 v54, 16, v85
	v_and_b32_e32 v55, 0xffff0000, v85
	v_pk_fma_f32 v[66:67], v[34:35], v[34:35], v[66:67]
	v_mul_f32_e32 v37, v32, v32
	v_mul_f32_e32 v85, v33, v33
	v_and_b32_e32 v71, 0xffff0000, v71
	v_mul_f32_e32 v62, v70, v70
	v_mov_b32_e32 v84, v36
	v_and_b32_e32 v80, 0xffff0000, v58
	v_lshlrev_b32_e32 v38, 16, v59
	v_and_b32_e32 v39, 0xffff0000, v59
	v_pk_add_f32 v[66:67], v[66:67], v[66:67] op_sel_hi:[0,1]
	v_pk_fma_f32 v[86:87], v[70:71], v[70:71], v[62:63] op_sel_hi:[1,1,0]
	v_pk_add_f32 v[84:85], v[36:37], v[84:85]
	v_mul_f32_e32 v86, v80, v80
	v_mul_f32_e32 v64, v38, v38
	v_mul_f32_e32 v66, v39, v39
	v_mul_f32_e32 v88, v36, v36
	v_mov_b32_e32 v89, v85
	v_pk_add_f32 v[84:85], v[88:89], v[86:87]
	v_pk_add_f32 v[64:65], v[64:65], v[66:67]
	v_and_b32_e32 v67, 0xffff0000, v61
	v_pk_add_f32 v[64:65], v[84:85], v[64:65]
	v_and_b32_e32 v66, 0xffff0000, v60
	v_pk_add_f32 v[84:85], v[64:65], v[64:65] op_sel_hi:[0,1]
	v_lshlrev_b32_e32 v65, 16, v61
	v_lshlrev_b32_e32 v64, 16, v60
	v_pk_mul_f32 v[60:61], v[66:67], v[66:67]
	v_lshlrev_b32_e32 v58, 16, v82
	v_pk_fma_f32 v[60:61], v[64:65], v[64:65], v[60:61]
	v_and_b32_e32 v59, 0xffff0000, v82
	v_pk_add_f32 v[86:87], v[60:61], v[60:61] op_sel_hi:[0,1]
	v_lshlrev_b32_e32 v60, 16, v83
	v_mul_f32_e32 v57, v58, v58
	v_mul_f32_e32 v89, v59, v59
	v_and_b32_e32 v61, 0xffff0000, v83
	v_mul_f32_e32 v62, v60, v60
	v_mov_b32_e32 v88, v56
	v_pk_fma_f32 v[82:83], v[60:61], v[60:61], v[62:63] op_sel_hi:[1,1,0]
	v_pk_add_f32 v[88:89], v[56:57], v[88:89]
	v_mul_f32_e32 v82, v63, v63
	v_mul_f32_e32 v86, v54, v54
	v_mul_f32_e32 v84, v55, v55
	v_mul_f32_e32 v90, v56, v56
	v_mov_b32_e32 v91, v89
	v_pk_add_f32 v[82:83], v[90:91], v[82:83]
	v_pk_add_f32 v[84:85], v[86:87], v[84:85]
	v_mov_b32_e32 v90, v72
	v_pk_add_f32 v[82:83], v[82:83], v[84:85]
	v_mov_b32_e32 v91, v74
	v_add_f32_e32 v37, v82, v83
	ds_bpermute_b32 v57, v230, v37
	v_mov_b32_e32 v74, v73
	s_waitcnt lgkmcnt(0)
	v_add_f32_e32 v37, v37, v57
	ds_bpermute_b32 v57, v231, v37
	s_waitcnt lgkmcnt(0)
	v_add_f32_e32 v37, v37, v57
	ds_bpermute_b32 v57, v232, v37
	s_waitcnt lgkmcnt(0)
	v_add_f32_e32 v37, v37, v57
	ds_bpermute_b32 v57, v233, v37
	s_waitcnt lgkmcnt(0)
	v_add_f32_e32 v37, v37, v57
	ds_bpermute_b32 v57, v234, v37
	s_waitcnt lgkmcnt(0)
	v_add_f32_e32 v37, v37, v57
	ds_bpermute_b32 v57, v235, v37
	s_waitcnt lgkmcnt(0)
	v_add_f32_e32 v37, v37, v57
	v_fmamk_f32 v37, v37, 0x3a000000, v219
	v_cmp_gt_f32_e32 vcc, s4, v37
	v_mul_f32_e32 v57, 0x4f800000, v37
	s_nop 0
	v_cndmask_b32_e32 v37, v37, v57, vcc
	v_sqrt_f32_e32 v57, v37
	s_nop 0
	v_add_u32_e32 v62, -1, v57
	v_fma_f32 v81, -v62, v57, v37
	v_cmp_ge_f32_e64 s[4:5], 0, v81
	v_add_u32_e32 v81, 1, v57
	s_nop 0
	v_cndmask_b32_e64 v62, v57, v62, s[4:5]
	v_fma_f32 v57, -v81, v57, v37
	v_cmp_lt_f32_e64 s[4:5], 0, v57
	s_nop 1
	v_cndmask_b32_e64 v57, v62, v81, s[4:5]
	v_mul_f32_e32 v62, 0x37800000, v57
	v_cndmask_b32_e32 v57, v57, v62, vcc
	v_cmp_class_f32_e32 vcc, v37, v220
	s_nop 1
	v_cndmask_b32_e32 v37, v57, v37, vcc
	v_div_scale_f32 v57, s[4:5], v37, v37, 1.0
	v_rcp_f32_e32 v62, v57
	s_nop 0
	v_fma_f32 v81, -v57, v62, 1.0
	v_fmac_f32_e32 v62, v81, v62
	v_div_scale_f32 v81, vcc, 1.0, v37, 1.0
	v_mul_f32_e32 v82, v81, v62
	v_fma_f32 v83, -v57, v82, v81
	v_fmac_f32_e32 v82, v83, v62
	v_fma_f32 v57, -v57, v82, v81
	v_div_fmas_f32 v57, v57, v62, v82
	v_mov_b64_e32 v[82:83], v[100:101]
	v_mov_b64_e32 v[84:85], v[102:103]
	v_mov_b64_e32 v[86:87], v[104:105]
	v_mov_b64_e32 v[88:89], v[106:107]
	v_div_fixup_f32 v62, v57, v37, 1.0
	s_waitcnt vmcnt(0)
	v_mov_b32_e32 v37, v80
	v_mov_b32_e32 v57, v63
	s_andn2_b64 vcc, exec, s[8:9]
	v_pk_mul_f32 v[72:73], v[82:83], v[74:75]
	v_pk_mul_f32 v[86:87], v[86:87], v[90:91]
	v_mov_b32_e32 v91, v78
	v_mov_b32_e32 v78, v77
	v_pk_mul_f32 v[74:75], v[84:85], v[78:79]
	v_mov_b32_e32 v90, v76
	v_pk_fma_f32 v[10:11], v[74:75], v[62:63], v[10:11] op_sel_hi:[1,0,1]
	v_pk_fma_f32 v[8:9], v[72:73], v[62:63], v[8:9] op_sel_hi:[1,0,1]
	v_mov_b64_e32 v[72:73], v[108:109]
	v_mov_b64_e32 v[74:75], v[110:111]
	v_mov_b64_e32 v[76:77], v[112:113]
	v_mov_b64_e32 v[78:79], v[114:115]
	v_mov_b32_e32 v83, v68
	v_mov_b32_e32 v68, v35
	v_mov_b32_e32 v82, v34
	v_pk_mul_f32 v[88:89], v[88:89], v[90:91]
	v_pk_fma_f32 v[12:13], v[86:87], v[62:63], v[12:13] op_sel_hi:[1,0,1]
	v_pk_fma_f32 v[14:15], v[88:89], v[62:63], v[14:15] op_sel_hi:[1,0,1]
	v_pk_mul_f32 v[32:33], v[72:73], v[32:33]
	v_pk_mul_f32 v[34:35], v[78:79], v[68:69]
	v_pk_fma_f32 v[16:17], v[32:33], v[62:63], v[16:17] op_sel_hi:[1,0,1]
	v_pk_fma_f32 v[22:23], v[34:35], v[62:63], v[22:23] op_sel_hi:[1,0,1]
	v_pk_mul_f32 v[34:35], v[74:75], v[70:71]
	v_pk_mul_f32 v[76:77], v[76:77], v[82:83]
	v_pk_fma_f32 v[18:19], v[34:35], v[62:63], v[18:19] op_sel_hi:[1,0,1]
	v_mov_b64_e32 v[32:33], v[116:117]
	v_mov_b64_e32 v[34:35], v[118:119]
	v_mov_b64_e32 v[68:69], v[120:121]
	v_mov_b64_e32 v[70:71], v[122:123]
	v_pk_fma_f32 v[20:21], v[76:77], v[62:63], v[20:21] op_sel_hi:[1,0,1]
	v_pk_mul_f32 v[36:37], v[68:69], v[36:37]
	s_nop 0
	v_pk_fma_f32 v[28:29], v[36:37], v[62:63], v[28:29] op_sel_hi:[1,0,1]
	v_mov_b32_e32 v36, v64
	v_mov_b32_e32 v37, v66
	v_mov_b32_e32 v66, v65
	v_pk_mul_f32 v[38:39], v[70:71], v[38:39]
	v_pk_mul_f32 v[32:33], v[32:33], v[36:37]
	v_pk_mul_f32 v[34:35], v[34:35], v[66:67]
	v_pk_fma_f32 v[30:31], v[38:39], v[62:63], v[30:31] op_sel_hi:[1,0,1]
	v_pk_fma_f32 v[26:27], v[34:35], v[62:63], v[26:27] op_sel_hi:[1,0,1]
	v_pk_fma_f32 v[24:25], v[32:33], v[62:63], v[24:25] op_sel_hi:[1,0,1]
	v_mov_b64_e32 v[32:33], v[124:125]
	v_mov_b64_e32 v[34:35], v[126:127]
	v_mov_b64_e32 v[36:37], v[128:129]
	v_mov_b64_e32 v[38:39], v[130:131]
	v_pk_mul_f32 v[32:33], v[32:33], v[56:57]
	v_pk_mul_f32 v[36:37], v[36:37], v[58:59]
	v_pk_mul_f32 v[38:39], v[38:39], v[60:61]
	v_pk_mul_f32 v[34:35], v[34:35], v[54:55]
	v_pk_fma_f32 v[6:7], v[38:39], v[62:63], v[6:7] op_sel_hi:[1,0,1]
	v_pk_fma_f32 v[4:5], v[36:37], v[62:63], v[4:5] op_sel_hi:[1,0,1]
	v_pk_fma_f32 v[2:3], v[34:35], v[62:63], v[2:3] op_sel_hi:[1,0,1]
	v_pk_fma_f32 v[0:1], v[32:33], v[62:63], v[0:1] op_sel_hi:[1,0,1]
	s_cbranch_vccnz .LBB0_748
	v_lshl_add_u64 v[32:33], s[18:19], 0, v[192:193]
	global_store_dwordx4 v[32:33], v[12:15], off
	global_store_dwordx4 v[32:33], v[8:11], off offset:16
	global_store_dwordx4 v[32:33], v[20:23], off offset:2048
	global_store_dwordx4 v[32:33], v[16:19], off offset:2064
	v_add_co_u32_e32 v32, vcc, 0x1000, v32
	s_nop 1
	v_addc_co_u32_e32 v33, vcc, 0, v33, vcc
	global_store_dwordx4 v[32:33], v[28:31], off
	global_store_dwordx4 v[32:33], v[24:27], off offset:16
	global_store_dwordx4 v[32:33], v[4:7], off offset:2048
	global_store_dwordx4 v[32:33], v[0:3], off offset:2064
